# group barrier: no separate wait between the flag store and the first poll
# baseline (speedup 1.0000x reference)
.LBB0_152:
	s_waitcnt vmcnt(0) lgkmcnt(0)
	v_mov_b32_e32 v1, 0
	v_mov_b32_e32 v3, 1
	v_readlane_b32 s20, v162, 62
	v_readlane_b32 s21, v164, 0
	v_readlane_b32 s22, v162, 63
	s_cmp_eq_u32 s20, 1
	s_cbranch_scc0 .Lxb21_glob
	s_and_b32 s4, s21, 15
	s_lshl_b32 s4, s4, 8
	s_bfe_u32 s5, s21, 0x20004
	s_lshl_b32 s5, s5, 5
	s_add_u32 s4, s4, s5
	s_add_u32 s4, s4, 0x480
	s_add_u32 s4, s84, s4
	s_addc_u32 s5, s85, 0
	s_add_u32 s22, s22, 1
	s_nop 1
	v_writelane_b32 v162, s22, 63
	s_lshr_b32 s21, s21, 6
	s_lshl_b32 s21, s21, 2
	v_mov_b32_e32 v5, s21
	v_mov_b32_e32 v6, s22
	global_store_dword v5, v6, s[4:5]
	s_mov_b32 s20, 0

.Lxb0_noinv:
	s_and_saveexec_b64 s[2:3], s[4:5]
	s_cbranch_execz .LBB0_246
	s_waitcnt vmcnt(0) lgkmcnt(0)
	v_readlane_b32 s20, v162, 62
	v_readlane_b32 s21, v164, 0
	v_readlane_b32 s22, v162, 63
	s_cmp_eq_u32 s20, 1
	s_cbranch_scc0 .Lxb0_glob
	s_and_b32 s4, s21, 15
	s_lshl_b32 s4, s4, 8
	s_bfe_u32 s5, s21, 0x20004
	s_lshl_b32 s5, s5, 5
	s_add_u32 s4, s4, s5
	s_add_u32 s4, s4, 0x480
	s_add_u32 s4, s84, s4
	s_addc_u32 s5, s85, 0
	s_add_u32 s22, s22, 1
	s_nop 1
	v_writelane_b32 v162, s22, 63
	s_lshr_b32 s21, s21, 6
	s_lshl_b32 s21, s21, 2
	v_mov_b32_e32 v5, s21
	v_mov_b32_e32 v6, s22
	global_store_dword v5, v6, s[4:5]
	s_mov_b32 s20, 0

.LBB0_1123:
	s_waitcnt vmcnt(0) lgkmcnt(0)
	v_readlane_b32 s20, v162, 62
	v_readlane_b32 s21, v164, 0
	v_readlane_b32 s22, v162, 63
	s_cmp_eq_u32 s20, 1
	s_cbranch_scc0 .Lxb11_glob
	s_and_b32 s4, s21, 15
	s_lshl_b32 s4, s4, 8
	s_bfe_u32 s5, s21, 0x20004
	s_lshl_b32 s5, s5, 5
	s_add_u32 s4, s4, s5
	s_add_u32 s4, s4, 0x480
	s_add_u32 s4, s84, s4
	s_addc_u32 s5, s85, 0
	s_add_u32 s22, s22, 1
	s_nop 1
	v_writelane_b32 v162, s22, 63
	s_lshr_b32 s21, s21, 6
	s_lshl_b32 s21, s21, 2
	v_mov_b32_e32 v5, s21
	v_mov_b32_e32 v6, s22
	global_store_dword v5, v6, s[4:5]
	s_mov_b32 s20, 0
